# phase 15 fused into phase 14 epilogue via stripe rendezvous; ss4 adds and reads as returning atomics
# baseline (speedup 1.0000x reference)
; __device__ __forceinline__ void phase0(const Params& P, unsigned char* smem) {
;     ...
;     const int gtid = blockIdx.x * NTHR + threadIdx.x, gsz = gridDim.x * NTHR;
;     for (int e = gtid; e < NT + 2 * NL; e += gsz) ((float*)(P.ws + OFF_SS))[e] = 0.f;
.LBB0_94:
	s_cmp_lg_u32 s33, 0
	s_cbranch_scc1 .Lp0_cnt_done
	s_mov_b64 s[2:3], exec
	s_mov_b64 exec, -1
	v_cmp_gt_u32_e32 vcc, 0x80, v168
	s_and_b64 exec, exec, vcc
	v_mov_b32_e32 v3, 0x1efa2000
	v_lshl_add_u32 v2, v168, 2, v3
	v_mov_b32_e32 v3, 0
	global_store_dword v2, v3, s[68:69]
	s_mov_b64 exec, s[2:3]

; #define PG8_STAGE(bufoff, gbase, voff) do { _Pragma("unroll") for (int _i = 0; _i < 2; ++_i) \
;         __builtin_amdgcn_global_load_lds((const unsigned*)((const char*)(gbase) + (voff)[_i]), (PG8_LAS unsigned*)(lds + (bufoff) + ldsw + _i * 8192), 16, 0, 0); } while (0)
; #define PG8_LDA(dst, b, h) do { _Pragma("unroll") for (int m = 0; m < 4; ++m) _Pragma("unroll") for (int k = 0; k < 2; ++k) dst[m][k] = *(const PG8_LAS bf16x8*)(lds + PG8_SA(b, h) + aoff + m * 2048 + k * 1024); } while (0)
; #define PG8_LDB(dst, b, h) do { _Pragma("unroll") for (int n = 0; n < 2; ++n) _Pragma("unroll") for (int k = 0; k < 2; ++k) dst[n][k] = *(const PG8_LAS bf16x8*)(lds + PG8_SB(b, h) + boff + n * 2048 + k * 1024); } while (0)
; #define PG8_MMA(ai, bj, At, Bt) do { __builtin_amdgcn_s_setprio(1); _Pragma("unroll") for (int m = 0; m < 4; ++m) _Pragma("unroll") for (int n = 0; n < 2; ++n) _Pragma("unroll") for (int k = 0; k < 2; ++k) \
;         acc[ai][bj][m][n] = __builtin_amdgcn_mfma_f32_16x16x32_bf16(Bt[n][k], At[m][k], acc[ai][bj][m][n], 0, 0, 0); __builtin_amdgcn_s_setprio(0); } while (0)
; #define PG8_WAIT_V(n) asm volatile("s_waitcnt vmcnt(" #n ")" ::: "memory")
; #define PG8_WAIT_L(n) asm volatile("s_waitcnt lgkmcnt(" #n ")" ::: "memory")
; template <class Epi>
; __device__ __forceinline__ void gemm_phase(PG8_LAS unsigned char* lds, const GemmD g, const Epi& E) {
;     ...
;         for (int t = 0; t < nt; t += 2) {
;             const bool last = (t == nt - 2);
;             const char* a1 = cA + (size_t)(t + 1) * kstep;
;             const char* a2 = last ? nA : cA + (size_t)(t + 2) * kstep; const char* b2 = last ? nB : cB + (size_t)(t + 2) * kstep;
;             const char* a3 = a2 + kstep; const char* b3 = b2 + kstep;
;             PG8_LDB(B0, 0, 0); PG8_SCHED; PG8_LDA(At, 0, 0); PG8_STAGE(PG8_SA(1, 1), a1 + hstepA, voffA);
;             PG8_WAIT_L(8); PG8_BAR; PG8_WAIT_L(0); PG8_MMA(0, 0, At, B0); PG8_BAR; PG8_SCHED;
;             PG8_LDB(B1, 0, 1); PG8_STAGE(PG8_SB(0, 0), b2, voffB);
;             PG8_BAR; PG8_WAIT_L(0); PG8_MMA(0, 1, At, B1); PG8_BAR;
;             PG8_LDA(At, 0, 1); PG8_STAGE(PG8_SA(0, 0), a2, voffA);
;             PG8_BAR; PG8_WAIT_L(0); PG8_MMA(1, 0, At, B0); PG8_BAR; PG8_SCHED;
;             PG8_STAGE(PG8_SB(0, 1), b2 + hstepB, voffB);
;             PG8_WAIT_V(6); PG8_BAR; PG8_MMA(1, 1, At, B1); PG8_BAR;
.LBB0_1699:
	ds_read_b128 v[128:131], v179
	ds_read_b128 v[132:135], v179 offset:1024
	ds_read_b128 v[154:157], v179 offset:2048
	ds_read_b128 v[158:161], v179 offset:3072
	s_add_u32 s16, s14, 0xfff50080
	s_addc_u32 s17, s15, -1
	s_cmp_eq_u32 s49, 40
	s_cselect_b32 s19, s1, s17
	s_cselect_b32 s18, s0, s16
	s_cselect_b32 s17, s7, s48
	s_cselect_b32 s16, s6, s47
	s_mov_b32 m0, s38
	v_lshl_add_u64 v[204:205], s[14:15], 0, v[146:147]
	ds_read_b128 v[162:165], v180
	ds_read_b128 v[166:169], v180 offset:1024
	ds_read_b128 v[172:175], v180 offset:2048
	ds_read_b128 v[184:187], v180 offset:3072
	ds_read_b128 v[188:191], v180 offset:4096
	ds_read_b128 v[192:195], v180 offset:5120
	ds_read_b128 v[196:199], v180 offset:6144
	ds_read_b128 v[200:203], v180 offset:7168
	global_load_lds_dwordx4 v[204:205], off
	v_lshl_add_u64 v[204:205], s[14:15], 0, v[148:149]
	s_mov_b32 m0, s39
	s_nop 0
	global_load_lds_dwordx4 v[204:205], off
	s_waitcnt lgkmcnt(8)
	s_barrier
	s_waitcnt lgkmcnt(0)
	s_setprio 1
	s_waitcnt lgkmcnt(0)
	v_mfma_f32_16x16x32_bf16 v[124:127], v[128:131], v[162:165], v[124:127]
	v_mfma_f32_16x16x32_bf16 v[120:123], v[154:157], v[162:165], v[120:123]
	v_mfma_f32_16x16x32_bf16 v[108:111], v[128:131], v[172:175], v[108:111]
	v_mfma_f32_16x16x32_bf16 v[104:107], v[154:157], v[172:175], v[104:107]
	v_mfma_f32_16x16x32_bf16 v[92:95], v[128:131], v[188:191], v[92:95]
	v_mfma_f32_16x16x32_bf16 v[88:91], v[154:157], v[188:191], v[88:91]
	v_mfma_f32_16x16x32_bf16 v[76:79], v[128:131], v[196:199], v[76:79]
	v_mfma_f32_16x16x32_bf16 v[72:75], v[154:157], v[196:199], v[72:75]
	v_mfma_f32_16x16x32_bf16 v[124:127], v[132:135], v[166:169], v[124:127]
	v_mfma_f32_16x16x32_bf16 v[120:123], v[158:161], v[166:169], v[120:123]
	v_mfma_f32_16x16x32_bf16 v[108:111], v[132:135], v[184:187], v[108:111]
	v_mfma_f32_16x16x32_bf16 v[104:107], v[158:161], v[184:187], v[104:107]
	v_mfma_f32_16x16x32_bf16 v[92:95], v[132:135], v[192:195], v[92:95]
	v_mfma_f32_16x16x32_bf16 v[88:91], v[158:161], v[192:195], v[88:91]
	v_mfma_f32_16x16x32_bf16 v[76:79], v[132:135], v[200:203], v[76:79]
	v_mfma_f32_16x16x32_bf16 v[72:75], v[158:161], v[200:203], v[72:75]
	s_setprio 0
	s_barrier
	s_mov_b32 m0, s40
	v_lshl_add_u64 v[220:221], s[16:17], 0, v[138:139]
	ds_read_b128 v[204:207], v181
	ds_read_b128 v[208:211], v181 offset:1024
	ds_read_b128 v[212:215], v181 offset:2048
	ds_read_b128 v[216:219], v181 offset:3072
	global_load_lds_dwordx4 v[220:221], off
	v_lshl_add_u64 v[222:223], s[16:17], 0, v[142:143]
	s_mov_b32 m0, s41
	s_nop 0
	global_load_lds_dwordx4 v[222:223], off
	s_barrier
	s_waitcnt lgkmcnt(0)
	s_setprio 1
	s_waitcnt lgkmcnt(0)
	v_mfma_f32_16x16x32_bf16 v[116:119], v[204:207], v[162:165], v[116:119]
	v_mfma_f32_16x16x32_bf16 v[112:115], v[212:215], v[162:165], v[112:115]
	v_mfma_f32_16x16x32_bf16 v[100:103], v[204:207], v[172:175], v[100:103]
	v_mfma_f32_16x16x32_bf16 v[96:99], v[212:215], v[172:175], v[96:99]
	v_mfma_f32_16x16x32_bf16 v[84:87], v[204:207], v[188:191], v[84:87]
	v_mfma_f32_16x16x32_bf16 v[80:83], v[212:215], v[188:191], v[80:83]
	v_mfma_f32_16x16x32_bf16 v[68:71], v[204:207], v[196:199], v[68:71]
	v_mfma_f32_16x16x32_bf16 v[64:67], v[212:215], v[196:199], v[64:67]
	v_mfma_f32_16x16x32_bf16 v[116:119], v[208:211], v[166:169], v[116:119]
	v_mfma_f32_16x16x32_bf16 v[112:115], v[216:219], v[166:169], v[112:115]
	v_mfma_f32_16x16x32_bf16 v[100:103], v[208:211], v[184:187], v[100:103]
	v_mfma_f32_16x16x32_bf16 v[96:99], v[216:219], v[184:187], v[96:99]
	v_mfma_f32_16x16x32_bf16 v[84:87], v[208:211], v[192:195], v[84:87]
	v_mfma_f32_16x16x32_bf16 v[80:83], v[216:219], v[192:195], v[80:83]
	v_mfma_f32_16x16x32_bf16 v[68:71], v[208:211], v[200:203], v[68:71]
	v_mfma_f32_16x16x32_bf16 v[64:67], v[216:219], v[200:203], v[64:67]
	s_setprio 0
	s_mov_b32 m0, s26
	v_lshl_add_u64 v[224:225], s[18:19], 0, v[136:137]
	s_barrier
	ds_read_b128 v[162:165], v180 offset:16384
	ds_read_b128 v[166:169], v180 offset:17408
	ds_read_b128 v[172:175], v180 offset:18432
	ds_read_b128 v[184:187], v180 offset:19456
	ds_read_b128 v[188:191], v180 offset:20480
	ds_read_b128 v[192:195], v180 offset:21504
	ds_read_b128 v[196:199], v180 offset:22528
	ds_read_b128 v[200:203], v180 offset:23552
	global_load_lds_dwordx4 v[224:225], off
	v_lshl_add_u64 v[226:227], s[18:19], 0, v[140:141]
	s_mov_b32 m0, s27
	s_nop 0
	global_load_lds_dwordx4 v[226:227], off
	s_barrier
	s_waitcnt lgkmcnt(0)
	s_setprio 1
	s_waitcnt lgkmcnt(0)
	v_mfma_f32_16x16x32_bf16 v[60:63], v[128:131], v[162:165], v[60:63]
	v_mfma_f32_16x16x32_bf16 v[56:59], v[154:157], v[162:165], v[56:59]
	v_mfma_f32_16x16x32_bf16 v[44:47], v[128:131], v[172:175], v[44:47]
	v_mfma_f32_16x16x32_bf16 v[40:43], v[154:157], v[172:175], v[40:43]
	v_mfma_f32_16x16x32_bf16 v[28:31], v[128:131], v[188:191], v[28:31]
	v_mfma_f32_16x16x32_bf16 v[24:27], v[154:157], v[188:191], v[24:27]
	v_mfma_f32_16x16x32_bf16 v[12:15], v[128:131], v[196:199], v[12:15]
	v_mfma_f32_16x16x32_bf16 v[8:11], v[154:157], v[196:199], v[8:11]
	v_mfma_f32_16x16x32_bf16 v[60:63], v[132:135], v[166:169], v[60:63]
	v_mfma_f32_16x16x32_bf16 v[56:59], v[158:161], v[166:169], v[56:59]
	v_mfma_f32_16x16x32_bf16 v[44:47], v[132:135], v[184:187], v[44:47]
	v_mfma_f32_16x16x32_bf16 v[40:43], v[158:161], v[184:187], v[40:43]
	v_mfma_f32_16x16x32_bf16 v[28:31], v[132:135], v[192:195], v[28:31]
	v_mfma_f32_16x16x32_bf16 v[24:27], v[158:161], v[192:195], v[24:27]
	v_mfma_f32_16x16x32_bf16 v[12:15], v[132:135], v[200:203], v[12:15]
	v_mfma_f32_16x16x32_bf16 v[8:11], v[158:161], v[200:203], v[8:11]
	s_setprio 0
	s_barrier
; #define PG8_STAGE(bufoff, gbase, voff) do { _Pragma("unroll") for (int _i = 0; _i < 2; ++_i) \
;         __builtin_amdgcn_global_load_lds((const unsigned*)((const char*)(gbase) + (voff)[_i]), (PG8_LAS unsigned*)(lds + (bufoff) + ldsw + _i * 8192), 16, 0, 0); } while (0)
; #define PG8_LDA(dst, b, h) do { _Pragma("unroll") for (int m = 0; m < 4; ++m) _Pragma("unroll") for (int k = 0; k < 2; ++k) dst[m][k] = *(const PG8_LAS bf16x8*)(lds + PG8_SA(b, h) + aoff + m * 2048 + k * 1024); } while (0)
; #define PG8_LDB(dst, b, h) do { _Pragma("unroll") for (int n = 0; n < 2; ++n) _Pragma("unroll") for (int k = 0; k < 2; ++k) dst[n][k] = *(const PG8_LAS bf16x8*)(lds + PG8_SB(b, h) + boff + n * 2048 + k * 1024); } while (0)
; #define PG8_MMA(ai, bj, At, Bt) do { __builtin_amdgcn_s_setprio(1); _Pragma("unroll") for (int m = 0; m < 4; ++m) _Pragma("unroll") for (int n = 0; n < 2; ++n) _Pragma("unroll") for (int k = 0; k < 2; ++k) \
;         acc[ai][bj][m][n] = __builtin_amdgcn_mfma_f32_16x16x32_bf16(Bt[n][k], At[m][k], acc[ai][bj][m][n], 0, 0, 0); __builtin_amdgcn_s_setprio(0); } while (0)
; #define PG8_WAIT_V(n) asm volatile("s_waitcnt vmcnt(" #n ")" ::: "memory")
; #define PG8_WAIT_L(n) asm volatile("s_waitcnt lgkmcnt(" #n ")" ::: "memory")
; #define PG8_BAR __builtin_amdgcn_s_barrier()
; #define PG8_SCHED __builtin_amdgcn_sched_barrier(0)
; template <class Epi>
; __device__ __forceinline__ void gemm_phase(PG8_LAS unsigned char* lds, const GemmD g, const Epi& E) {
;     ...
;             PG8_STAGE(PG8_SB(0, 1), b2 + hstepB, voffB);
;             PG8_WAIT_V(6); PG8_BAR; PG8_MMA(1, 1, At, B1); PG8_BAR;
;             PG8_LDB(B0, 1, 0); PG8_SCHED; PG8_LDA(At, 1, 0); PG8_STAGE(PG8_SA(0, 1), a2 + hstepA, voffA);
;             PG8_WAIT_L(8); PG8_BAR; PG8_WAIT_L(0); PG8_MMA(0, 0, At, B0); PG8_BAR; PG8_SCHED;
;             PG8_LDB(B1, 1, 1); PG8_STAGE(PG8_SB(1, 0), b3, voffB);
;             PG8_BAR; PG8_WAIT_L(0); PG8_MMA(0, 1, At, B1); PG8_BAR;
;             PG8_LDA(At, 1, 1); PG8_STAGE(PG8_SA(1, 0), a3, voffA);
;             PG8_BAR; PG8_WAIT_L(0); PG8_MMA(1, 0, At, B0); PG8_BAR; PG8_SCHED;
;             PG8_STAGE(PG8_SB(1, 1), b3 + hstepB, voffB);
;             PG8_WAIT_V(6); PG8_BAR; PG8_MMA(1, 1, At, B1); PG8_BAR;
	s_add_u32 s50, s16, 0xb0000
	s_addc_u32 s51, s17, 0
	s_mov_b32 m0, s42
	v_lshl_add_u64 v[128:129], s[50:51], 0, v[138:139]
	global_load_lds_dwordx4 v[128:129], off
	v_lshl_add_u64 v[128:129], s[50:51], 0, v[142:143]
	s_add_i32 m0, s42, 0x2000
	s_nop 0
	global_load_lds_dwordx4 v[128:129], off
	s_waitcnt vmcnt(6)
	s_barrier
	s_setprio 1
	v_mfma_f32_16x16x32_bf16 v[52:55], v[204:207], v[162:165], v[52:55]
	v_mfma_f32_16x16x32_bf16 v[48:51], v[212:215], v[162:165], v[48:51]
	v_mfma_f32_16x16x32_bf16 v[36:39], v[204:207], v[172:175], v[36:39]
	v_mfma_f32_16x16x32_bf16 v[32:35], v[212:215], v[172:175], v[32:35]
	v_mfma_f32_16x16x32_bf16 v[20:23], v[204:207], v[188:191], v[20:23]
	v_mfma_f32_16x16x32_bf16 v[16:19], v[212:215], v[188:191], v[16:19]
	v_mfma_f32_16x16x32_bf16 v[4:7], v[204:207], v[196:199], v[4:7]
	v_mfma_f32_16x16x32_bf16 v[0:3], v[212:215], v[196:199], v[0:3]
	v_mfma_f32_16x16x32_bf16 v[52:55], v[208:211], v[166:169], v[52:55]
	v_mfma_f32_16x16x32_bf16 v[48:51], v[216:219], v[166:169], v[48:51]
	v_mfma_f32_16x16x32_bf16 v[36:39], v[208:211], v[184:187], v[36:39]
	v_mfma_f32_16x16x32_bf16 v[32:35], v[216:219], v[184:187], v[32:35]
	v_mfma_f32_16x16x32_bf16 v[20:23], v[208:211], v[192:195], v[20:23]
	v_mfma_f32_16x16x32_bf16 v[16:19], v[216:219], v[192:195], v[16:19]
	v_mfma_f32_16x16x32_bf16 v[4:7], v[208:211], v[200:203], v[4:7]
	v_mfma_f32_16x16x32_bf16 v[0:3], v[216:219], v[200:203], v[0:3]
	s_setprio 0
	s_add_i32 s50, 16, 0x18000
	v_add_u32_e32 v158, s50, v177
	s_barrier
	ds_read_b128 v[128:131], v158
	ds_read_b128 v[132:135], v158 offset:1024
	ds_read_b128 v[154:157], v158 offset:2048
	ds_read_b128 v[158:161], v158 offset:3072
	s_add_u32 s18, s18, 0xb0000
	s_addc_u32 s19, s19, 0
	s_mov_b32 m0, s28
	v_lshl_add_u64 v[204:205], s[18:19], 0, v[136:137]
	ds_read_b128 v[162:165], v180 offset:32768
	ds_read_b128 v[166:169], v180 offset:33792
	ds_read_b128 v[172:175], v180 offset:34816
	ds_read_b128 v[184:187], v180 offset:35840
	ds_read_b128 v[188:191], v180 offset:36864
	ds_read_b128 v[192:195], v180 offset:37888
	ds_read_b128 v[196:199], v180 offset:38912
	ds_read_b128 v[200:203], v180 offset:39936
	global_load_lds_dwordx4 v[204:205], off
	v_lshl_add_u64 v[204:205], s[18:19], 0, v[140:141]
	s_mov_b32 m0, s29
	s_nop 0
	global_load_lds_dwordx4 v[204:205], off
	s_waitcnt lgkmcnt(8)
	s_barrier
	s_waitcnt lgkmcnt(0)
	s_setprio 1
	s_waitcnt lgkmcnt(0)
	v_mfma_f32_16x16x32_bf16 v[124:127], v[128:131], v[162:165], v[124:127]
	v_mfma_f32_16x16x32_bf16 v[120:123], v[154:157], v[162:165], v[120:123]
	v_mfma_f32_16x16x32_bf16 v[108:111], v[128:131], v[172:175], v[108:111]
	v_mfma_f32_16x16x32_bf16 v[104:107], v[154:157], v[172:175], v[104:107]
	v_mfma_f32_16x16x32_bf16 v[92:95], v[128:131], v[188:191], v[92:95]
	v_mfma_f32_16x16x32_bf16 v[88:91], v[154:157], v[188:191], v[88:91]
	v_mfma_f32_16x16x32_bf16 v[76:79], v[128:131], v[196:199], v[76:79]
	v_mfma_f32_16x16x32_bf16 v[72:75], v[154:157], v[196:199], v[72:75]
	v_mfma_f32_16x16x32_bf16 v[124:127], v[132:135], v[166:169], v[124:127]
	v_mfma_f32_16x16x32_bf16 v[120:123], v[158:161], v[166:169], v[120:123]
	v_mfma_f32_16x16x32_bf16 v[108:111], v[132:135], v[184:187], v[108:111]
	v_mfma_f32_16x16x32_bf16 v[104:107], v[158:161], v[184:187], v[104:107]
	v_mfma_f32_16x16x32_bf16 v[92:95], v[132:135], v[192:195], v[92:95]
	v_mfma_f32_16x16x32_bf16 v[88:91], v[158:161], v[192:195], v[88:91]
	v_mfma_f32_16x16x32_bf16 v[76:79], v[132:135], v[200:203], v[76:79]
	v_mfma_f32_16x16x32_bf16 v[72:75], v[158:161], v[200:203], v[72:75]
	s_setprio 0
	s_barrier
	s_add_i32 s18, 16, 0x1c000
	s_add_i32 s19, s50, s25
	v_add_u32_e32 v183, s18, v177
	v_lshl_add_u64 v[220:221], v[220:221], 0, s[10:11]
	s_mov_b32 m0, s19
	ds_read_b128 v[204:207], v183
	ds_read_b128 v[208:211], v183 offset:1024
	ds_read_b128 v[212:215], v183 offset:2048
	ds_read_b128 v[216:219], v183 offset:3072
	global_load_lds_dwordx4 v[220:221], off
	v_lshl_add_u64 v[220:221], v[222:223], 0, s[10:11]
	s_add_i32 m0, s19, 0x2000
	s_nop 0
	global_load_lds_dwordx4 v[220:221], off
	s_barrier
	s_waitcnt lgkmcnt(0)
	s_setprio 1
	s_waitcnt lgkmcnt(0)
	v_mfma_f32_16x16x32_bf16 v[116:119], v[204:207], v[162:165], v[116:119]
	v_mfma_f32_16x16x32_bf16 v[112:115], v[212:215], v[162:165], v[112:115]
	v_mfma_f32_16x16x32_bf16 v[100:103], v[204:207], v[172:175], v[100:103]
	v_mfma_f32_16x16x32_bf16 v[96:99], v[212:215], v[172:175], v[96:99]
	v_mfma_f32_16x16x32_bf16 v[84:87], v[204:207], v[188:191], v[84:87]
	v_mfma_f32_16x16x32_bf16 v[80:83], v[212:215], v[188:191], v[80:83]
	v_mfma_f32_16x16x32_bf16 v[68:71], v[204:207], v[196:199], v[68:71]
	v_mfma_f32_16x16x32_bf16 v[64:67], v[212:215], v[196:199], v[64:67]
	v_mfma_f32_16x16x32_bf16 v[116:119], v[208:211], v[166:169], v[116:119]
	v_mfma_f32_16x16x32_bf16 v[112:115], v[216:219], v[166:169], v[112:115]
	v_mfma_f32_16x16x32_bf16 v[100:103], v[208:211], v[184:187], v[100:103]
	v_mfma_f32_16x16x32_bf16 v[96:99], v[216:219], v[184:187], v[96:99]
	v_mfma_f32_16x16x32_bf16 v[84:87], v[208:211], v[192:195], v[84:87]
	v_mfma_f32_16x16x32_bf16 v[80:83], v[216:219], v[192:195], v[80:83]
	v_mfma_f32_16x16x32_bf16 v[68:71], v[208:211], v[200:203], v[68:71]
	v_mfma_f32_16x16x32_bf16 v[64:67], v[216:219], v[200:203], v[64:67]
	s_setprio 0
	s_mov_b32 m0, s31
	v_lshl_add_u64 v[220:221], v[224:225], 0, s[10:11]
	s_barrier
	ds_read_b128 v[162:165], v180 offset:49152
	ds_read_b128 v[166:169], v180 offset:50176
	ds_read_b128 v[172:175], v180 offset:51200
	ds_read_b128 v[184:187], v180 offset:52224
	ds_read_b128 v[188:191], v180 offset:53248
	ds_read_b128 v[192:195], v180 offset:54272
	ds_read_b128 v[196:199], v180 offset:55296
	ds_read_b128 v[200:203], v180 offset:56320
	global_load_lds_dwordx4 v[220:221], off
	v_lshl_add_u64 v[220:221], v[226:227], 0, s[10:11]
	s_mov_b32 m0, s34
	s_nop 0
	global_load_lds_dwordx4 v[220:221], off
	s_barrier
; #define PG8_BAR __builtin_amdgcn_s_barrier()
; template <class Epi>
; __device__ __forceinline__ void gemm_phase(PG8_LAS unsigned char* lds, const GemmD g, const Epi& E) {
;     ...
;             PG8_WAIT_V(6); PG8_BAR; PG8_MMA(1, 1, At, B1); PG8_BAR;
;             PG8_LDB(B0, 1, 0); PG8_SCHED; PG8_LDA(At, 1, 0); PG8_STAGE(PG8_SA(0, 1), a2 + hstepA, voffA);
;             PG8_WAIT_L(8); PG8_BAR; PG8_WAIT_L(0); PG8_MMA(0, 0, At, B0); PG8_BAR; PG8_SCHED;
;             PG8_LDB(B1, 1, 1); PG8_STAGE(PG8_SB(1, 0), b3, voffB);
;             PG8_BAR; PG8_WAIT_L(0); PG8_MMA(0, 1, At, B1); PG8_BAR;
;             PG8_LDA(At, 1, 1); PG8_STAGE(PG8_SA(1, 0), a3, voffA);
;             PG8_BAR; PG8_WAIT_L(0); PG8_MMA(1, 0, At, B0); PG8_BAR; PG8_SCHED;
;             PG8_STAGE(PG8_SB(1, 1), b3 + hstepB, voffB);
;             PG8_WAIT_V(6); PG8_BAR; PG8_MMA(1, 1, At, B1); PG8_BAR;
;     __device__ __forceinline__ void operator()(const AccT& acc, const Unit& u, int wr, int wc, int fr, int fq) const {
;         constexpr int GJ = MODE == 0 ? 2 : (MODE == 1 ? 5 : 8), SJ = MODE == 0 ? 4 : 7;
;         constexpr float COEF = MODE == 1 ? 1.f : 0.5f;
;         const float* mb = mod + ((256 * u.pm) >> 13) * 9216;
;         const int nb = 256 * u.pn + 32 * wc + 8 * fq;
;         f32x4 gate[2][2]; uint2 gmp[2][2];
; #pragma unroll
;         for (int bj = 0; bj < 2; ++bj)
; #pragma unroll
;             for (int nn = 0; nn < 2; ++nn) {
;                 const int n = nb + 128 * bj + 4 * nn;
;                 gate[bj][nn] = *(const f32x4*)(mb + GJ * 1024 + n) * COEF;
;                 if (MODE < 2) { const f32x4 t = *(const f32x4*)(gnext + n) * (*(const f32x4*)(mb + SJ * 1024 + n) + 1.f); gmp[bj][nn] = make_uint2(pk2(t[0], t[1]), pk2(t[2], t[3])); }
;             }
; #pragma unroll
;         for (int ai = 0; ai < 2; ++ai)
; #pragma unroll
;         for (int mh = 0; mh < 2; ++mh) {
;             const size_t rb = (size_t)(256 * u.pm + 128 * ai + 64 * wr + 32 * mh + fr) * 1024 + nb;
;             f32x4 xf[MODE == 0 ? 2 : 1][2][2]; uint4 xh[MODE == 0 ? 1 : 2][2];
; #pragma unroll
;             for (int mm = 0; mm < 2; ++mm)
; #pragma unroll
;                 for (int bj = 0; bj < 2; ++bj) {
;                     const size_t idx = rb + (size_t)mm * 16 * 1024 + 128 * bj;
;                     if (MODE == 0) { xf[mm][bj][0] = *(const f32x4*)(x + idx); xf[mm][bj][1] = *(const f32x4*)(x + idx + 4); }
	s_waitcnt lgkmcnt(0)
	s_setprio 1
	s_waitcnt lgkmcnt(0)
	v_mfma_f32_16x16x32_bf16 v[60:63], v[128:131], v[162:165], v[60:63]
	v_mfma_f32_16x16x32_bf16 v[56:59], v[154:157], v[162:165], v[56:59]
	v_mfma_f32_16x16x32_bf16 v[44:47], v[128:131], v[172:175], v[44:47]
	v_mfma_f32_16x16x32_bf16 v[40:43], v[154:157], v[172:175], v[40:43]
	v_mfma_f32_16x16x32_bf16 v[28:31], v[128:131], v[188:191], v[28:31]
	v_mfma_f32_16x16x32_bf16 v[24:27], v[154:157], v[188:191], v[24:27]
	v_mfma_f32_16x16x32_bf16 v[12:15], v[128:131], v[196:199], v[12:15]
	v_mfma_f32_16x16x32_bf16 v[8:11], v[154:157], v[196:199], v[8:11]
	v_mfma_f32_16x16x32_bf16 v[60:63], v[132:135], v[166:169], v[60:63]
	v_mfma_f32_16x16x32_bf16 v[56:59], v[158:161], v[166:169], v[56:59]
	v_mfma_f32_16x16x32_bf16 v[44:47], v[132:135], v[184:187], v[44:47]
	v_mfma_f32_16x16x32_bf16 v[40:43], v[158:161], v[184:187], v[40:43]
	v_mfma_f32_16x16x32_bf16 v[28:31], v[132:135], v[192:195], v[28:31]
	v_mfma_f32_16x16x32_bf16 v[24:27], v[158:161], v[192:195], v[24:27]
	v_mfma_f32_16x16x32_bf16 v[12:15], v[132:135], v[200:203], v[12:15]
	v_mfma_f32_16x16x32_bf16 v[8:11], v[158:161], v[200:203], v[8:11]
	s_setprio 0
	s_barrier
	s_add_u32 s16, s16, 0xb0080
	s_addc_u32 s17, s17, 0
	s_add_i32 s18, s18, s25
	v_lshl_add_u64 v[128:129], s[16:17], 0, v[138:139]
	s_mov_b32 m0, s18
	s_nop 0
	global_load_lds_dwordx4 v[128:129], off
	v_lshl_add_u64 v[128:129], s[16:17], 0, v[142:143]
	s_add_i32 m0, s18, 0x2000
	s_nop 0
	global_load_lds_dwordx4 v[128:129], off
	s_waitcnt vmcnt(6)
	s_barrier
	s_setprio 1
	v_mfma_f32_16x16x32_bf16 v[52:55], v[204:207], v[162:165], v[52:55]
	v_mfma_f32_16x16x32_bf16 v[48:51], v[212:215], v[162:165], v[48:51]
	v_mfma_f32_16x16x32_bf16 v[36:39], v[204:207], v[172:175], v[36:39]
	v_mfma_f32_16x16x32_bf16 v[32:35], v[212:215], v[172:175], v[32:35]
	v_mfma_f32_16x16x32_bf16 v[20:23], v[204:207], v[188:191], v[20:23]
	v_mfma_f32_16x16x32_bf16 v[16:19], v[212:215], v[188:191], v[16:19]
	v_mfma_f32_16x16x32_bf16 v[4:7], v[204:207], v[196:199], v[4:7]
	v_mfma_f32_16x16x32_bf16 v[0:3], v[212:215], v[196:199], v[0:3]
	v_mfma_f32_16x16x32_bf16 v[52:55], v[208:211], v[166:169], v[52:55]
	v_mfma_f32_16x16x32_bf16 v[48:51], v[216:219], v[166:169], v[48:51]
	v_mfma_f32_16x16x32_bf16 v[36:39], v[208:211], v[184:187], v[36:39]
	v_mfma_f32_16x16x32_bf16 v[32:35], v[216:219], v[184:187], v[32:35]
	v_mfma_f32_16x16x32_bf16 v[20:23], v[208:211], v[192:195], v[20:23]
	v_mfma_f32_16x16x32_bf16 v[16:19], v[216:219], v[192:195], v[16:19]
	v_mfma_f32_16x16x32_bf16 v[4:7], v[208:211], v[200:203], v[4:7]
	v_mfma_f32_16x16x32_bf16 v[0:3], v[216:219], v[200:203], v[0:3]
	s_setprio 0
	s_add_i32 s49, s49, 2
	s_add_u32 s14, s14, 0x100
	s_addc_u32 s15, s15, 0
	s_add_u32 s47, s47, 0x100
	s_addc_u32 s48, s48, 0
	s_cmp_lt_u32 s49, 42
	s_barrier
	s_cbranch_scc1 .LBB0_1699
	s_lshr_b32 s14, s45, 5
	s_mulk_i32 s14, 0x2400
	s_ashr_i32 s15, s14, 31
	s_lshl_b64 s[14:15], s[14:15], 2
	s_add_u32 s14, s68, s14
	v_lshl_or_b32 v172, s46, 8, v178
	s_addc_u32 s15, s69, s15
	v_ashrrev_i32_e32 v173, 31, v172
	v_lshl_add_u64 v[128:129], v[172:173], 2, s[14:15]
	s_lshl_b32 s14, s45, 8
	v_lshl_add_u64 v[130:131], v[128:129], 0, s[12:13]
	v_add_u32_e32 v174, s14, v176
	v_ashrrev_i32_e32 v175, 31, v174
	global_load_dwordx4 v[166:169], v[130:131], off
	global_load_dwordx4 v[162:165], v[130:131], off offset:16
	global_load_dwordx4 v[158:161], v[130:131], off offset:512
	global_load_dwordx4 v[154:157], v[130:131], off offset:528
	v_lshlrev_b64 v[128:129], 10, v[174:175]
	v_lshl_add_u64 v[196:197], v[128:129], 0, v[172:173]
	v_lshl_add_u64 v[198:199], v[196:197], 1, s[8:9]
	s_ashr_i32 s15, s14, 31
	v_lshl_add_u64 v[200:201], s[14:15], 2, v[144:145]
	s_mov_b32 s98, 0x8000
	s_mov_b32 s99, 0
	s_mov_b32 s100, 0x28000
	s_mov_b32 s101, 0
	global_load_dwordx4 v[228:231], v[198:199], off
	global_load_dwordx4 v[232:235], v[198:199], off offset:256
	v_lshl_add_u64 v[198:199], v[198:199], 0, s[98:99]
	global_load_dwordx4 v[236:239], v[198:199], off
	global_load_dwordx4 v[240:243], v[198:199], off offset:256
	v_lshl_add_u64 v[198:199], v[198:199], 0, s[98:99]
	global_load_dwordx4 v[244:247], v[198:199], off
	global_load_dwordx4 v[184:187], v[198:199], off offset:256
	v_lshl_add_u64 v[198:199], v[198:199], 0, s[98:99]
	global_load_dwordx4 v[188:191], v[198:199], off
	global_load_dwordx4 v[192:195], v[198:199], off offset:256
	v_lshl_add_u64 v[198:199], v[198:199], 0, s[100:101]
	v_xor_b32_e32 v128, 16, v182
	v_xor_b32_e32 v129, 32, v182
	v_lshlrev_b32_e32 v128, 2, v128
	v_lshlrev_b32_e32 v129, 2, v129
	s_waitcnt vmcnt(8)
	v_pk_mul_f32 v[166:167], v[166:167], 0.5 op_sel_hi:[1,0]
	v_pk_mul_f32 v[168:169], v[168:169], 0.5 op_sel_hi:[1,0]
	v_pk_mul_f32 v[162:163], v[162:163], 0.5 op_sel_hi:[1,0]
	v_pk_mul_f32 v[164:165], v[164:165], 0.5 op_sel_hi:[1,0]
	v_pk_mul_f32 v[158:159], v[158:159], 0.5 op_sel_hi:[1,0]
	v_pk_mul_f32 v[160:161], v[160:161], 0.5 op_sel_hi:[1,0]
	v_pk_mul_f32 v[154:155], v[154:155], 0.5 op_sel_hi:[1,0]
	v_pk_mul_f32 v[156:157], v[156:157], 0.5 op_sel_hi:[1,0]
	s_waitcnt vmcnt(6)
; __device__ __forceinline__ unsigned pk2(float a, float b) { const f32x2_t v = {a, b}; const bf16x2_t r = __builtin_convertvector(v, bf16x2_t); return __builtin_bit_cast(unsigned, r); }
; __device__ __forceinline__ float bflo(unsigned u) { return __uint_as_float(u << 16); }
; __device__ __forceinline__ float bfhi(unsigned u) { return __uint_as_float(u & 0xffff0000u); }
;     __device__ __forceinline__ void operator()(const AccT& acc, const Unit& u, int wr, int wc, int fr, int fq) const {
;     ...
; #pragma unroll
;             for (int mm = 0; mm < 2; ++mm) {
;                 float part = 0.f;
; #pragma unroll
;                 for (int bj = 0; bj < 2; ++bj) {
;                     const size_t idx = rb + (size_t)mm * 16 * 1024 + 128 * bj;
;                     f32x4 x0, x1;
;                     if (MODE == 0) { x0 = xf[mm][bj][0]; x1 = xf[mm][bj][1]; }
;                     else { const uint4 h4 = xh[mm][bj]; x0 = (f32x4){bflo(h4.x), bfhi(h4.x), bflo(h4.y), bfhi(h4.y)}; x1 = (f32x4){bflo(h4.z), bfhi(h4.z), bflo(h4.w), bfhi(h4.w)}; }
;                     const f32x4 n0 = x0 + gate[bj][0] * acc[ai][bj][2 * mh + mm][0], n1 = x1 + gate[bj][1] * acc[ai][bj][2 * mh + mm][1];
;                     part += (n0[0] * n0[0] + n0[1] * n0[1] + n0[2] * n0[2] + n0[3] * n0[3]) + (n1[0] * n1[0] + n1[1] * n1[1] + n1[2] * n1[2] + n1[3] * n1[3]);
;                     if (MODE < 2) {
;                         *(uint4*)(XRb + idx) = make_uint4(pk2(n0[0], n0[1]), pk2(n0[2], n0[3]), pk2(n1[0], n1[1]), pk2(n1[2], n1[3]));
;                         const f32x4 g0 = {bflo(gmp[bj][0].x), bfhi(gmp[bj][0].x), bflo(gmp[bj][0].y), bfhi(gmp[bj][0].y)}, g1 = {bflo(gmp[bj][1].x), bfhi(gmp[bj][1].x), bflo(gmp[bj][1].y), bfhi(gmp[bj][1].y)};
;                         const f32x4 h0 = n0 * g0, h1 = n1 * g1;
;                         *(uint4*)(Hn + idx) = make_uint4(pk2(h0[0], h0[1]), pk2(h0[2], h0[3]), pk2(h1[0], h1[1]), pk2(h1[2], h1[3]));
;                     } else { *(f32x4*)(out + idx) = n0; *(f32x4*)(out + idx + 4) = n1; }
;                 }
;                 part += __shfl_xor(part, 16); part += __shfl_xor(part, 32);
;                 if (fq == 0) (void)__hip_atomic_fetch_add(ss + 256 * u.pm + 128 * ai + 64 * wr + 32 * mh + 16 * mm + fr, part, __ATOMIC_RELAXED, __HIP_MEMORY_SCOPE_AGENT);
;             }
	v_lshlrev_b32_e32 v130, 16, v228
	v_and_b32_e32 v131, 0xffff0000, v228
	v_pk_fma_f32 v[124:125], v[124:125], v[166:167], v[130:131]
	v_lshlrev_b32_e32 v132, 16, v229
	v_and_b32_e32 v133, 0xffff0000, v229
	v_pk_fma_f32 v[126:127], v[126:127], v[168:169], v[132:133]
	v_lshlrev_b32_e32 v130, 16, v230
	v_and_b32_e32 v131, 0xffff0000, v230
	v_pk_fma_f32 v[120:121], v[120:121], v[162:163], v[130:131]
	v_lshlrev_b32_e32 v132, 16, v231
	v_and_b32_e32 v133, 0xffff0000, v231
	v_pk_fma_f32 v[122:123], v[122:123], v[164:165], v[132:133]
	v_lshlrev_b32_e32 v130, 16, v232
	v_and_b32_e32 v131, 0xffff0000, v232
	v_pk_fma_f32 v[116:117], v[116:117], v[158:159], v[130:131]
	v_lshlrev_b32_e32 v132, 16, v233
	v_and_b32_e32 v133, 0xffff0000, v233
	v_pk_fma_f32 v[118:119], v[118:119], v[160:161], v[132:133]
	v_lshlrev_b32_e32 v130, 16, v234
	v_and_b32_e32 v131, 0xffff0000, v234
	v_pk_fma_f32 v[112:113], v[112:113], v[154:155], v[130:131]
	v_lshlrev_b32_e32 v132, 16, v235
	v_and_b32_e32 v133, 0xffff0000, v235
	v_pk_fma_f32 v[114:115], v[114:115], v[156:157], v[132:133]
	global_load_dwordx4 v[228:231], v[198:199], off
	global_load_dwordx4 v[232:235], v[198:199], off offset:256
	v_lshl_add_u64 v[198:199], v[198:199], 0, s[98:99]
	v_mul_f32_e32 v134, v125, v125
	v_mul_f32_e32 v135, v121, v121
	v_mul_f32_e32 v183, v117, v117
	v_mul_f32_e32 v248, v113, v113
	v_fmac_f32_e32 v134, v124, v124
	v_fmac_f32_e32 v135, v120, v120
	v_fmac_f32_e32 v183, v116, v116
	v_fmac_f32_e32 v248, v112, v112
	v_fmac_f32_e32 v134, v126, v126
	v_fmac_f32_e32 v135, v122, v122
	v_fmac_f32_e32 v183, v118, v118
	v_fmac_f32_e32 v248, v114, v114
	v_fmac_f32_e32 v134, v127, v127
	v_fmac_f32_e32 v135, v123, v123
	v_fmac_f32_e32 v183, v119, v119
	v_fmac_f32_e32 v248, v115, v115
	v_add_f32_e32 v134, v134, v135
	v_add_f32_e32 v183, v183, v248
	v_add_f32_e32 v174, v134, v183
	ds_bpermute_b32 v249, v128, v174
	s_waitcnt vmcnt(6)
	v_lshlrev_b32_e32 v130, 16, v236
	v_and_b32_e32 v131, 0xffff0000, v236
	v_pk_fma_f32 v[108:109], v[108:109], v[166:167], v[130:131]
	v_lshlrev_b32_e32 v132, 16, v237
	v_and_b32_e32 v133, 0xffff0000, v237
	v_pk_fma_f32 v[110:111], v[110:111], v[168:169], v[132:133]
	v_lshlrev_b32_e32 v130, 16, v238
	v_and_b32_e32 v131, 0xffff0000, v238
	v_pk_fma_f32 v[104:105], v[104:105], v[162:163], v[130:131]
	v_lshlrev_b32_e32 v132, 16, v239
	v_and_b32_e32 v133, 0xffff0000, v239
	v_pk_fma_f32 v[106:107], v[106:107], v[164:165], v[132:133]
	s_waitcnt lgkmcnt(0)
	v_add_f32_e32 v174, v174, v249
	ds_bpermute_b32 v249, v129, v174
	v_lshlrev_b32_e32 v130, 16, v240
	v_and_b32_e32 v131, 0xffff0000, v240
	v_pk_fma_f32 v[100:101], v[100:101], v[158:159], v[130:131]
	v_lshlrev_b32_e32 v132, 16, v241
	v_and_b32_e32 v133, 0xffff0000, v241
	v_pk_fma_f32 v[102:103], v[102:103], v[160:161], v[132:133]
	v_lshlrev_b32_e32 v130, 16, v242
	v_and_b32_e32 v131, 0xffff0000, v242
	v_pk_fma_f32 v[96:97], v[96:97], v[154:155], v[130:131]
	v_lshlrev_b32_e32 v132, 16, v243
	v_and_b32_e32 v133, 0xffff0000, v243
	v_pk_fma_f32 v[98:99], v[98:99], v[156:157], v[132:133]
	global_load_dwordx4 v[236:239], v[198:199], off
	global_load_dwordx4 v[240:243], v[198:199], off offset:256
	v_lshl_add_u64 v[198:199], v[198:199], 0, s[98:99]
	v_mul_f32_e32 v134, v109, v109
	v_mul_f32_e32 v135, v105, v105
	v_mul_f32_e32 v183, v101, v101
	v_mul_f32_e32 v248, v97, v97
	v_fmac_f32_e32 v134, v108, v108
	v_fmac_f32_e32 v135, v104, v104
	v_fmac_f32_e32 v183, v100, v100
	v_fmac_f32_e32 v248, v96, v96
	v_fmac_f32_e32 v134, v110, v110
	v_fmac_f32_e32 v135, v106, v106
	v_fmac_f32_e32 v183, v102, v102
	v_fmac_f32_e32 v248, v98, v98
	v_fmac_f32_e32 v134, v111, v111
	v_fmac_f32_e32 v135, v107, v107
	v_fmac_f32_e32 v183, v103, v103
	v_fmac_f32_e32 v248, v99, v99
	v_add_f32_e32 v134, v134, v135
	v_add_f32_e32 v183, v183, v248
	s_waitcnt lgkmcnt(0)
	v_add_f32_e32 v174, v174, v249
	s_mov_b64 exec, s[2:3]
	global_atomic_add_f32 v202, v[200:201], v174, off sc0
	s_mov_b64 exec, -1
	v_add_f32_e32 v175, v134, v183
	ds_bpermute_b32 v249, v128, v175
	s_waitcnt vmcnt(7)
	v_lshlrev_b32_e32 v130, 16, v244
	v_and_b32_e32 v131, 0xffff0000, v244
	v_pk_fma_f32 v[92:93], v[92:93], v[166:167], v[130:131]
	v_lshlrev_b32_e32 v132, 16, v245
	v_and_b32_e32 v133, 0xffff0000, v245
	v_pk_fma_f32 v[94:95], v[94:95], v[168:169], v[132:133]
	v_lshlrev_b32_e32 v130, 16, v246
	v_and_b32_e32 v131, 0xffff0000, v246
	v_pk_fma_f32 v[88:89], v[88:89], v[162:163], v[130:131]
	v_lshlrev_b32_e32 v132, 16, v247
	v_and_b32_e32 v133, 0xffff0000, v247
	v_pk_fma_f32 v[90:91], v[90:91], v[164:165], v[132:133]
	s_waitcnt lgkmcnt(0)
	v_add_f32_e32 v175, v175, v249
	ds_bpermute_b32 v249, v129, v175
	v_lshlrev_b32_e32 v130, 16, v184
	v_and_b32_e32 v131, 0xffff0000, v184
	v_pk_fma_f32 v[84:85], v[84:85], v[158:159], v[130:131]
	v_lshlrev_b32_e32 v132, 16, v185
	v_and_b32_e32 v133, 0xffff0000, v185
	v_pk_fma_f32 v[86:87], v[86:87], v[160:161], v[132:133]
	v_lshlrev_b32_e32 v130, 16, v186
	v_and_b32_e32 v131, 0xffff0000, v186
	v_pk_fma_f32 v[80:81], v[80:81], v[154:155], v[130:131]
	v_lshlrev_b32_e32 v132, 16, v187
	v_and_b32_e32 v133, 0xffff0000, v187
	v_pk_fma_f32 v[82:83], v[82:83], v[156:157], v[132:133]
	global_load_dwordx4 v[244:247], v[198:199], off
	global_load_dwordx4 v[184:187], v[198:199], off offset:256
	v_lshl_add_u64 v[198:199], v[198:199], 0, s[98:99]
	v_mul_f32_e32 v134, v93, v93
	v_mul_f32_e32 v135, v89, v89
	v_mul_f32_e32 v183, v85, v85
	v_mul_f32_e32 v248, v81, v81
	v_fmac_f32_e32 v134, v92, v92
	v_fmac_f32_e32 v135, v88, v88
	v_fmac_f32_e32 v183, v84, v84
	v_fmac_f32_e32 v248, v80, v80
	v_fmac_f32_e32 v134, v94, v94
	v_fmac_f32_e32 v135, v90, v90
	v_fmac_f32_e32 v183, v86, v86
	v_fmac_f32_e32 v248, v82, v82
	v_fmac_f32_e32 v134, v95, v95
	v_fmac_f32_e32 v135, v91, v91
	v_fmac_f32_e32 v183, v87, v87
	v_fmac_f32_e32 v248, v83, v83
	v_add_f32_e32 v134, v134, v135
	v_add_f32_e32 v183, v183, v248
	s_waitcnt lgkmcnt(0)
; __device__ __forceinline__ unsigned pk2(float a, float b) { const f32x2_t v = {a, b}; const bf16x2_t r = __builtin_convertvector(v, bf16x2_t); return __builtin_bit_cast(unsigned, r); }
; __device__ __forceinline__ float bflo(unsigned u) { return __uint_as_float(u << 16); }
; __device__ __forceinline__ float bfhi(unsigned u) { return __uint_as_float(u & 0xffff0000u); }
;     __device__ __forceinline__ void operator()(const AccT& acc, const Unit& u, int wr, int wc, int fr, int fq) const {
;     ...
; #pragma unroll
;             for (int mm = 0; mm < 2; ++mm) {
;                 float part = 0.f;
; #pragma unroll
;                 for (int bj = 0; bj < 2; ++bj) {
;                     const size_t idx = rb + (size_t)mm * 16 * 1024 + 128 * bj;
;                     f32x4 x0, x1;
;                     if (MODE == 0) { x0 = xf[mm][bj][0]; x1 = xf[mm][bj][1]; }
;                     else { const uint4 h4 = xh[mm][bj]; x0 = (f32x4){bflo(h4.x), bfhi(h4.x), bflo(h4.y), bfhi(h4.y)}; x1 = (f32x4){bflo(h4.z), bfhi(h4.z), bflo(h4.w), bfhi(h4.w)}; }
;                     const f32x4 n0 = x0 + gate[bj][0] * acc[ai][bj][2 * mh + mm][0], n1 = x1 + gate[bj][1] * acc[ai][bj][2 * mh + mm][1];
;                     part += (n0[0] * n0[0] + n0[1] * n0[1] + n0[2] * n0[2] + n0[3] * n0[3]) + (n1[0] * n1[0] + n1[1] * n1[1] + n1[2] * n1[2] + n1[3] * n1[3]);
;                     if (MODE < 2) {
;                         *(uint4*)(XRb + idx) = make_uint4(pk2(n0[0], n0[1]), pk2(n0[2], n0[3]), pk2(n1[0], n1[1]), pk2(n1[2], n1[3]));
;                         const f32x4 g0 = {bflo(gmp[bj][0].x), bfhi(gmp[bj][0].x), bflo(gmp[bj][0].y), bfhi(gmp[bj][0].y)}, g1 = {bflo(gmp[bj][1].x), bfhi(gmp[bj][1].x), bflo(gmp[bj][1].y), bfhi(gmp[bj][1].y)};
;                         const f32x4 h0 = n0 * g0, h1 = n1 * g1;
;                         *(uint4*)(Hn + idx) = make_uint4(pk2(h0[0], h0[1]), pk2(h0[2], h0[3]), pk2(h1[0], h1[1]), pk2(h1[2], h1[3]));
;                     } else { *(f32x4*)(out + idx) = n0; *(f32x4*)(out + idx + 4) = n1; }
;                 }
;                 part += __shfl_xor(part, 16); part += __shfl_xor(part, 32);
;                 if (fq == 0) (void)__hip_atomic_fetch_add(ss + 256 * u.pm + 128 * ai + 64 * wr + 32 * mh + 16 * mm + fr, part, __ATOMIC_RELAXED, __HIP_MEMORY_SCOPE_AGENT);
;             }
	v_add_f32_e32 v175, v175, v249
	s_mov_b64 exec, s[2:3]
	global_atomic_add_f32 v202, v[200:201], v175, off offset:64 sc0
	s_mov_b64 exec, -1
	v_add_f32_e32 v174, v134, v183
	ds_bpermute_b32 v249, v128, v174
	s_waitcnt vmcnt(8)
	v_lshlrev_b32_e32 v130, 16, v188
	v_and_b32_e32 v131, 0xffff0000, v188
	v_pk_fma_f32 v[76:77], v[76:77], v[166:167], v[130:131]
	v_lshlrev_b32_e32 v132, 16, v189
	v_and_b32_e32 v133, 0xffff0000, v189
	v_pk_fma_f32 v[78:79], v[78:79], v[168:169], v[132:133]
	v_lshlrev_b32_e32 v130, 16, v190
	v_and_b32_e32 v131, 0xffff0000, v190
	v_pk_fma_f32 v[72:73], v[72:73], v[162:163], v[130:131]
	v_lshlrev_b32_e32 v132, 16, v191
	v_and_b32_e32 v133, 0xffff0000, v191
	v_pk_fma_f32 v[74:75], v[74:75], v[164:165], v[132:133]
	s_waitcnt lgkmcnt(0)
	v_add_f32_e32 v174, v174, v249
	ds_bpermute_b32 v249, v129, v174
	v_lshlrev_b32_e32 v130, 16, v192
	v_and_b32_e32 v131, 0xffff0000, v192
	v_pk_fma_f32 v[68:69], v[68:69], v[158:159], v[130:131]
	v_lshlrev_b32_e32 v132, 16, v193
	v_and_b32_e32 v133, 0xffff0000, v193
	v_pk_fma_f32 v[70:71], v[70:71], v[160:161], v[132:133]
	v_lshlrev_b32_e32 v130, 16, v194
	v_and_b32_e32 v131, 0xffff0000, v194
	v_pk_fma_f32 v[64:65], v[64:65], v[154:155], v[130:131]
	v_lshlrev_b32_e32 v132, 16, v195
	v_and_b32_e32 v133, 0xffff0000, v195
	v_pk_fma_f32 v[66:67], v[66:67], v[156:157], v[132:133]
	global_load_dwordx4 v[188:191], v[198:199], off
	global_load_dwordx4 v[192:195], v[198:199], off offset:256
	v_mul_f32_e32 v134, v77, v77
	v_mul_f32_e32 v135, v73, v73
	v_mul_f32_e32 v183, v69, v69
	v_mul_f32_e32 v248, v65, v65
	v_fmac_f32_e32 v134, v76, v76
	v_fmac_f32_e32 v135, v72, v72
	v_fmac_f32_e32 v183, v68, v68
	v_fmac_f32_e32 v248, v64, v64
	v_fmac_f32_e32 v134, v78, v78
	v_fmac_f32_e32 v135, v74, v74
	v_fmac_f32_e32 v183, v70, v70
	v_fmac_f32_e32 v248, v66, v66
	v_fmac_f32_e32 v134, v79, v79
	v_fmac_f32_e32 v135, v75, v75
	v_fmac_f32_e32 v183, v71, v71
	v_fmac_f32_e32 v248, v67, v67
	v_add_f32_e32 v134, v134, v135
	v_add_f32_e32 v183, v183, v248
	s_waitcnt lgkmcnt(0)
	v_add_f32_e32 v174, v174, v249
	s_mov_b64 exec, s[2:3]
	global_atomic_add_f32 v202, v[200:201], v174, off offset:128 sc0
	s_mov_b64 exec, -1
	v_add_f32_e32 v175, v134, v183
	ds_bpermute_b32 v249, v128, v175
	s_waitcnt vmcnt(9)
	v_lshlrev_b32_e32 v130, 16, v228
	v_and_b32_e32 v131, 0xffff0000, v228
	v_pk_fma_f32 v[60:61], v[60:61], v[166:167], v[130:131]
	v_lshlrev_b32_e32 v132, 16, v229
	v_and_b32_e32 v133, 0xffff0000, v229
	v_pk_fma_f32 v[62:63], v[62:63], v[168:169], v[132:133]
	v_lshlrev_b32_e32 v130, 16, v230
	v_and_b32_e32 v131, 0xffff0000, v230
	v_pk_fma_f32 v[56:57], v[56:57], v[162:163], v[130:131]
	v_lshlrev_b32_e32 v132, 16, v231
	v_and_b32_e32 v133, 0xffff0000, v231
	v_pk_fma_f32 v[58:59], v[58:59], v[164:165], v[132:133]
	s_waitcnt lgkmcnt(0)
	v_add_f32_e32 v175, v175, v249
	ds_bpermute_b32 v249, v129, v175
	v_lshlrev_b32_e32 v130, 16, v232
	v_and_b32_e32 v131, 0xffff0000, v232
	v_pk_fma_f32 v[52:53], v[52:53], v[158:159], v[130:131]
	v_lshlrev_b32_e32 v132, 16, v233
	v_and_b32_e32 v133, 0xffff0000, v233
	v_pk_fma_f32 v[54:55], v[54:55], v[160:161], v[132:133]
	v_lshlrev_b32_e32 v130, 16, v234
	v_and_b32_e32 v131, 0xffff0000, v234
	v_pk_fma_f32 v[48:49], v[48:49], v[154:155], v[130:131]
	v_lshlrev_b32_e32 v132, 16, v235
	v_and_b32_e32 v133, 0xffff0000, v235
	v_pk_fma_f32 v[50:51], v[50:51], v[156:157], v[132:133]
	v_mul_f32_e32 v134, v61, v61
	v_mul_f32_e32 v135, v57, v57
	v_mul_f32_e32 v183, v53, v53
	v_mul_f32_e32 v248, v49, v49
	v_fmac_f32_e32 v134, v60, v60
	v_fmac_f32_e32 v135, v56, v56
	v_fmac_f32_e32 v183, v52, v52
	v_fmac_f32_e32 v248, v48, v48
	v_fmac_f32_e32 v134, v62, v62
	v_fmac_f32_e32 v135, v58, v58
	v_fmac_f32_e32 v183, v54, v54
	v_fmac_f32_e32 v248, v50, v50
	v_fmac_f32_e32 v134, v63, v63
	v_fmac_f32_e32 v135, v59, v59
	v_fmac_f32_e32 v183, v55, v55
	v_fmac_f32_e32 v248, v51, v51
	v_add_f32_e32 v134, v134, v135
	v_add_f32_e32 v183, v183, v248
	s_waitcnt lgkmcnt(0)
	v_add_f32_e32 v175, v175, v249
	s_mov_b64 exec, s[2:3]
	global_atomic_add_f32 v202, v[200:201], v175, off offset:192 sc0
	s_mov_b64 exec, -1
	v_add_f32_e32 v174, v134, v183
	ds_bpermute_b32 v249, v128, v174
	s_waitcnt vmcnt(8)
	v_lshlrev_b32_e32 v130, 16, v236
	v_and_b32_e32 v131, 0xffff0000, v236
	v_pk_fma_f32 v[44:45], v[44:45], v[166:167], v[130:131]
	v_lshlrev_b32_e32 v132, 16, v237
	v_and_b32_e32 v133, 0xffff0000, v237
	v_pk_fma_f32 v[46:47], v[46:47], v[168:169], v[132:133]
	v_lshlrev_b32_e32 v130, 16, v238
	v_and_b32_e32 v131, 0xffff0000, v238
	v_pk_fma_f32 v[40:41], v[40:41], v[162:163], v[130:131]
	v_lshlrev_b32_e32 v132, 16, v239
	v_and_b32_e32 v133, 0xffff0000, v239
	v_pk_fma_f32 v[42:43], v[42:43], v[164:165], v[132:133]
	s_waitcnt lgkmcnt(0)
	v_add_f32_e32 v174, v174, v249
	ds_bpermute_b32 v249, v129, v174
	v_lshlrev_b32_e32 v130, 16, v240
	v_and_b32_e32 v131, 0xffff0000, v240
	v_pk_fma_f32 v[36:37], v[36:37], v[158:159], v[130:131]
	v_lshlrev_b32_e32 v132, 16, v241
	v_and_b32_e32 v133, 0xffff0000, v241
	v_pk_fma_f32 v[38:39], v[38:39], v[160:161], v[132:133]
	v_lshlrev_b32_e32 v130, 16, v242
	v_and_b32_e32 v131, 0xffff0000, v242
	v_pk_fma_f32 v[32:33], v[32:33], v[154:155], v[130:131]
	v_lshlrev_b32_e32 v132, 16, v243
	v_and_b32_e32 v133, 0xffff0000, v243
	v_pk_fma_f32 v[34:35], v[34:35], v[156:157], v[132:133]
	v_mul_f32_e32 v134, v45, v45
	v_mul_f32_e32 v135, v41, v41
	v_mul_f32_e32 v183, v37, v37
	v_mul_f32_e32 v248, v33, v33
	v_fmac_f32_e32 v134, v44, v44
	v_fmac_f32_e32 v135, v40, v40
	v_fmac_f32_e32 v183, v36, v36
	v_fmac_f32_e32 v248, v32, v32
	v_fmac_f32_e32 v134, v46, v46
	v_fmac_f32_e32 v135, v42, v42
	v_fmac_f32_e32 v183, v38, v38
	v_fmac_f32_e32 v248, v34, v34
	v_fmac_f32_e32 v134, v47, v47
	v_fmac_f32_e32 v135, v43, v43
	v_fmac_f32_e32 v183, v39, v39
	v_fmac_f32_e32 v248, v35, v35
	v_add_f32_e32 v134, v134, v135
	v_add_f32_e32 v183, v183, v248
	s_waitcnt lgkmcnt(0)
; __device__ __forceinline__ unsigned pk2(float a, float b) { const f32x2_t v = {a, b}; const bf16x2_t r = __builtin_convertvector(v, bf16x2_t); return __builtin_bit_cast(unsigned, r); }
; __device__ __forceinline__ float bflo(unsigned u) { return __uint_as_float(u << 16); }
; __device__ __forceinline__ void phase15(const Params& P) {
;     ...
;     f32x4 fn[4];
; #pragma unroll
;     for (int j = 0; j < 4; ++j) fn[j] = ((const f32x4*)P.in[32])[lane + 64 * j];
;     __device__ __forceinline__ void operator()(const AccT& acc, const Unit& u, int wr, int wc, int fr, int fq) const {
;     ...
; #pragma unroll
;             for (int mm = 0; mm < 2; ++mm) {
;                 float part = 0.f;
; #pragma unroll
;                 for (int bj = 0; bj < 2; ++bj) {
;                     const size_t idx = rb + (size_t)mm * 16 * 1024 + 128 * bj;
;                     f32x4 x0, x1;
;                     if (MODE == 0) { x0 = xf[mm][bj][0]; x1 = xf[mm][bj][1]; }
;                     else { const uint4 h4 = xh[mm][bj]; x0 = (f32x4){bflo(h4.x), bfhi(h4.x), bflo(h4.y), bfhi(h4.y)}; x1 = (f32x4){bflo(h4.z), bfhi(h4.z), bflo(h4.w), bfhi(h4.w)}; }
;                     const f32x4 n0 = x0 + gate[bj][0] * acc[ai][bj][2 * mh + mm][0], n1 = x1 + gate[bj][1] * acc[ai][bj][2 * mh + mm][1];
;                     part += (n0[0] * n0[0] + n0[1] * n0[1] + n0[2] * n0[2] + n0[3] * n0[3]) + (n1[0] * n1[0] + n1[1] * n1[1] + n1[2] * n1[2] + n1[3] * n1[3]);
;                     if (MODE < 2) {
;                         *(uint4*)(XRb + idx) = make_uint4(pk2(n0[0], n0[1]), pk2(n0[2], n0[3]), pk2(n1[0], n1[1]), pk2(n1[2], n1[3]));
;                         const f32x4 g0 = {bflo(gmp[bj][0].x), bfhi(gmp[bj][0].x), bflo(gmp[bj][0].y), bfhi(gmp[bj][0].y)}, g1 = {bflo(gmp[bj][1].x), bfhi(gmp[bj][1].x), bflo(gmp[bj][1].y), bfhi(gmp[bj][1].y)};
;                         const f32x4 h0 = n0 * g0, h1 = n1 * g1;
;                         *(uint4*)(Hn + idx) = make_uint4(pk2(h0[0], h0[1]), pk2(h0[2], h0[3]), pk2(h1[0], h1[1]), pk2(h1[2], h1[3]));
;                     } else { *(f32x4*)(out + idx) = n0; *(f32x4*)(out + idx + 4) = n1; }
;                 }
;                 part += __shfl_xor(part, 16); part += __shfl_xor(part, 32);
;                 if (fq == 0) (void)__hip_atomic_fetch_add(ss + 256 * u.pm + 128 * ai + 64 * wr + 32 * mh + 16 * mm + fr, part, __ATOMIC_RELAXED, __HIP_MEMORY_SCOPE_AGENT);
;             }
	v_add_f32_e32 v174, v174, v249
	s_mov_b64 exec, s[2:3]
	global_atomic_add_f32 v202, v[200:201], v174, off offset:512 sc0
	s_mov_b64 exec, -1
	v_add_f32_e32 v175, v134, v183
	ds_bpermute_b32 v249, v128, v175
	s_waitcnt vmcnt(6)
	v_lshlrev_b32_e32 v130, 16, v244
	v_and_b32_e32 v131, 0xffff0000, v244
	v_pk_fma_f32 v[28:29], v[28:29], v[166:167], v[130:131]
	v_lshlrev_b32_e32 v132, 16, v245
	v_and_b32_e32 v133, 0xffff0000, v245
	v_pk_fma_f32 v[30:31], v[30:31], v[168:169], v[132:133]
	v_lshlrev_b32_e32 v130, 16, v246
	v_and_b32_e32 v131, 0xffff0000, v246
	v_pk_fma_f32 v[24:25], v[24:25], v[162:163], v[130:131]
	v_lshlrev_b32_e32 v132, 16, v247
	v_and_b32_e32 v133, 0xffff0000, v247
	v_pk_fma_f32 v[26:27], v[26:27], v[164:165], v[132:133]
	s_waitcnt lgkmcnt(0)
	v_add_f32_e32 v175, v175, v249
	ds_bpermute_b32 v249, v129, v175
	v_lshlrev_b32_e32 v130, 16, v184
	v_and_b32_e32 v131, 0xffff0000, v184
	v_pk_fma_f32 v[20:21], v[20:21], v[158:159], v[130:131]
	v_lshlrev_b32_e32 v132, 16, v185
	v_and_b32_e32 v133, 0xffff0000, v185
	v_pk_fma_f32 v[22:23], v[22:23], v[160:161], v[132:133]
	v_lshlrev_b32_e32 v130, 16, v186
	v_and_b32_e32 v131, 0xffff0000, v186
	v_pk_fma_f32 v[16:17], v[16:17], v[154:155], v[130:131]
	v_lshlrev_b32_e32 v132, 16, v187
	v_and_b32_e32 v133, 0xffff0000, v187
	v_pk_fma_f32 v[18:19], v[18:19], v[156:157], v[132:133]
	v_mul_f32_e32 v134, v29, v29
	v_mul_f32_e32 v135, v25, v25
	v_mul_f32_e32 v183, v21, v21
	v_mul_f32_e32 v248, v17, v17
	v_fmac_f32_e32 v134, v28, v28
	v_fmac_f32_e32 v135, v24, v24
	v_fmac_f32_e32 v183, v20, v20
	v_fmac_f32_e32 v248, v16, v16
	v_fmac_f32_e32 v134, v30, v30
	v_fmac_f32_e32 v135, v26, v26
	v_fmac_f32_e32 v183, v22, v22
	v_fmac_f32_e32 v248, v18, v18
	v_fmac_f32_e32 v134, v31, v31
	v_fmac_f32_e32 v135, v27, v27
	v_fmac_f32_e32 v183, v23, v23
	v_fmac_f32_e32 v248, v19, v19
	v_add_f32_e32 v134, v134, v135
	v_add_f32_e32 v183, v183, v248
	s_waitcnt lgkmcnt(0)
	v_add_f32_e32 v175, v175, v249
	s_mov_b64 exec, s[2:3]
	global_atomic_add_f32 v202, v[200:201], v175, off offset:576 sc0
	s_mov_b64 exec, -1
	v_add_f32_e32 v174, v134, v183
	ds_bpermute_b32 v249, v128, v174
	s_waitcnt vmcnt(4)
	v_lshlrev_b32_e32 v130, 16, v188
	v_and_b32_e32 v131, 0xffff0000, v188
	v_pk_fma_f32 v[12:13], v[12:13], v[166:167], v[130:131]
	v_lshlrev_b32_e32 v132, 16, v189
	v_and_b32_e32 v133, 0xffff0000, v189
	v_pk_fma_f32 v[14:15], v[14:15], v[168:169], v[132:133]
	v_lshlrev_b32_e32 v130, 16, v190
	v_and_b32_e32 v131, 0xffff0000, v190
	v_pk_fma_f32 v[8:9], v[8:9], v[162:163], v[130:131]
	v_lshlrev_b32_e32 v132, 16, v191
	v_and_b32_e32 v133, 0xffff0000, v191
	v_pk_fma_f32 v[10:11], v[10:11], v[164:165], v[132:133]
	s_waitcnt lgkmcnt(0)
	v_add_f32_e32 v174, v174, v249
	ds_bpermute_b32 v249, v129, v174
	v_lshlrev_b32_e32 v130, 16, v192
	v_and_b32_e32 v131, 0xffff0000, v192
	v_pk_fma_f32 v[4:5], v[4:5], v[158:159], v[130:131]
	v_lshlrev_b32_e32 v132, 16, v193
	v_and_b32_e32 v133, 0xffff0000, v193
	v_pk_fma_f32 v[6:7], v[6:7], v[160:161], v[132:133]
	v_lshlrev_b32_e32 v130, 16, v194
	v_and_b32_e32 v131, 0xffff0000, v194
	v_pk_fma_f32 v[0:1], v[0:1], v[154:155], v[130:131]
	v_lshlrev_b32_e32 v132, 16, v195
	v_and_b32_e32 v133, 0xffff0000, v195
	v_pk_fma_f32 v[2:3], v[2:3], v[156:157], v[132:133]
	v_mul_f32_e32 v134, v13, v13
	v_mul_f32_e32 v135, v9, v9
	v_mul_f32_e32 v183, v5, v5
	v_mul_f32_e32 v248, v1, v1
	v_fmac_f32_e32 v134, v12, v12
	v_fmac_f32_e32 v135, v8, v8
	v_fmac_f32_e32 v183, v4, v4
	v_fmac_f32_e32 v248, v0, v0
	v_fmac_f32_e32 v134, v14, v14
	v_fmac_f32_e32 v135, v10, v10
	v_fmac_f32_e32 v183, v6, v6
	v_fmac_f32_e32 v248, v2, v2
	v_fmac_f32_e32 v134, v15, v15
	v_fmac_f32_e32 v135, v11, v11
	v_fmac_f32_e32 v183, v7, v7
	v_fmac_f32_e32 v248, v3, v3
	v_add_f32_e32 v134, v134, v135
	v_add_f32_e32 v183, v183, v248
	s_waitcnt lgkmcnt(0)
	v_add_f32_e32 v174, v174, v249
	s_mov_b64 exec, s[2:3]
	global_atomic_add_f32 v202, v[200:201], v174, off offset:640 sc0
	s_mov_b64 exec, -1
	v_add_f32_e32 v175, v134, v183
	ds_bpermute_b32 v249, v128, v175
	s_waitcnt lgkmcnt(0)
	v_add_f32_e32 v175, v175, v249
	ds_bpermute_b32 v249, v129, v175
	v_lshl_add_u64 v[130:131], v[172:173], 2, s[64:65]
	global_load_dwordx4 v[228:231], v[130:131], off
	global_load_dwordx4 v[232:235], v[130:131], off offset:16
	global_load_dwordx4 v[236:239], v[130:131], off offset:512
	global_load_dwordx4 v[240:243], v[130:131], off offset:528
	s_waitcnt lgkmcnt(0)
	v_add_f32_e32 v175, v175, v249
	s_mov_b64 exec, s[2:3]
	global_atomic_add_f32 v202, v[200:201], v175, off offset:704 sc0
	s_mov_b64 exec, -1
	s_waitcnt vmcnt(0)
	s_barrier
	s_cmp_lg_u32 s20, 0
	s_cbranch_scc1 .Lp14_norendezvous
	s_lshl_b32 s14, s45, 2
	s_add_u32 s14, s14, 0x1efa2000
	s_add_u32 s14, s68, s14
	s_addc_u32 s15, s69, 0
	v_mov_b32_e32 v130, 0
	v_mov_b32_e32 v131, 1
	s_mov_b64 exec, 1
	global_atomic_add v130, v131, s[14:15]
	s_mov_b32 s98, 0
.Lp14_spin:
	global_load_dword v131, v130, s[14:15] sc1
	s_waitcnt vmcnt(0)
	v_readfirstlane_b32 s99, v131
	s_add_u32 s98, s98, 1
	s_nop 1
	s_cmp_ge_u32 s99, 4
	s_cbranch_scc1 .Lp14_spun
	s_cmp_lt_u32 s98, 0x4000
	s_cbranch_scc0 .Lp14_spun
	s_sleep 2
	s_branch .Lp14_spin
.Lp14_spun:
	s_mov_b64 exec, -1
; __device__ __forceinline__ void phase15(const Params& P) {
;     ...
;     while (row < NL) {
;         f32x4 v[4]; const float sc = sn;
; #pragma unroll
;         for (int j = 0; j < 4; ++j) v[j] = vn[j];
;         const int nrow = row + stride;
;         if (nrow < NL) { sn = ss4[nrow];
; #pragma unroll
;             for (int j = 0; j < 4; ++j) vn[j] = ((const f32x4*)(P.out + (size_t)nrow * 1024))[lane + 64 * j]; }
;         const float rstd = rsqrtf(sc * (1.f / 1024.f) + 1e-6f);
;         f32x4* o = (f32x4*)(P.out + (size_t)row * 1024);
; #pragma unroll
;         for (int j = 0; j < 4; ++j) o[lane + 64 * j] = (v[j] * rstd) * fn[j];
;         row = nrow;
;     }
.Lp14_norendezvous:
	s_barrier
	v_mov_b32_e32 v203, 0
	global_atomic_add_f32 v244, v[200:201], v203, off sc0
	global_atomic_add_f32 v246, v[200:201], v203, off offset:64 sc0
	global_atomic_add_f32 v184, v[200:201], v203, off offset:128 sc0
	global_atomic_add_f32 v186, v[200:201], v203, off offset:192 sc0
	global_atomic_add_f32 v188, v[200:201], v203, off offset:512 sc0
	global_atomic_add_f32 v190, v[200:201], v203, off offset:576 sc0
	global_atomic_add_f32 v192, v[200:201], v203, off offset:640 sc0
	global_atomic_add_f32 v194, v[200:201], v203, off offset:704 sc0
	v_mov_b32_e32 v128, 0x358637bd
	v_lshl_add_u64 v[198:199], v[196:197], 2, s[66:67]
	s_mov_b32 s98, 0x10000
	s_mov_b32 s99, 0
	s_mov_b32 s100, 0x50000
	s_mov_b32 s101, 0
	s_waitcnt vmcnt(0)
	v_fmamk_f32 v244, v244, 0x3a800000, v128
	v_fmamk_f32 v246, v246, 0x3a800000, v128
	v_fmamk_f32 v184, v184, 0x3a800000, v128
	v_fmamk_f32 v186, v186, 0x3a800000, v128
	v_fmamk_f32 v188, v188, 0x3a800000, v128
	v_fmamk_f32 v190, v190, 0x3a800000, v128
	v_fmamk_f32 v192, v192, 0x3a800000, v128
	v_fmamk_f32 v194, v194, 0x3a800000, v128
	v_rsq_f32_e32 v244, v244
	v_rsq_f32_e32 v246, v246
	v_rsq_f32_e32 v184, v184
	v_rsq_f32_e32 v186, v186
	v_rsq_f32_e32 v188, v188
	v_rsq_f32_e32 v190, v190
	v_rsq_f32_e32 v192, v192
	v_rsq_f32_e32 v194, v194
	s_nop 0
	v_pk_mul_f32 v[124:125], v[124:125], v[244:245] op_sel_hi:[1,0]
	v_pk_mul_f32 v[126:127], v[126:127], v[244:245] op_sel_hi:[1,0]
	v_pk_mul_f32 v[120:121], v[120:121], v[244:245] op_sel_hi:[1,0]
	v_pk_mul_f32 v[122:123], v[122:123], v[244:245] op_sel_hi:[1,0]
	v_pk_mul_f32 v[116:117], v[116:117], v[244:245] op_sel_hi:[1,0]
	v_pk_mul_f32 v[118:119], v[118:119], v[244:245] op_sel_hi:[1,0]
	v_pk_mul_f32 v[112:113], v[112:113], v[244:245] op_sel_hi:[1,0]
	v_pk_mul_f32 v[114:115], v[114:115], v[244:245] op_sel_hi:[1,0]
	v_pk_mul_f32 v[124:125], v[228:229], v[124:125]
	v_pk_mul_f32 v[126:127], v[230:231], v[126:127]
	v_pk_mul_f32 v[120:121], v[232:233], v[120:121]
	v_pk_mul_f32 v[122:123], v[234:235], v[122:123]
	v_pk_mul_f32 v[116:117], v[236:237], v[116:117]
	v_pk_mul_f32 v[118:119], v[238:239], v[118:119]
	v_pk_mul_f32 v[112:113], v[240:241], v[112:113]
	v_pk_mul_f32 v[114:115], v[242:243], v[114:115]
	global_store_dwordx4 v[198:199], v[124:127], off
	global_store_dwordx4 v[198:199], v[120:123], off offset:16
	global_store_dwordx4 v[198:199], v[116:119], off offset:512
	global_store_dwordx4 v[198:199], v[112:115], off offset:528
	v_lshl_add_u64 v[198:199], v[198:199], 0, s[98:99]
	v_pk_mul_f32 v[108:109], v[108:109], v[246:247] op_sel_hi:[1,0]
	v_pk_mul_f32 v[110:111], v[110:111], v[246:247] op_sel_hi:[1,0]
	v_pk_mul_f32 v[104:105], v[104:105], v[246:247] op_sel_hi:[1,0]
	v_pk_mul_f32 v[106:107], v[106:107], v[246:247] op_sel_hi:[1,0]
	v_pk_mul_f32 v[100:101], v[100:101], v[246:247] op_sel_hi:[1,0]
	v_pk_mul_f32 v[102:103], v[102:103], v[246:247] op_sel_hi:[1,0]
	v_pk_mul_f32 v[96:97], v[96:97], v[246:247] op_sel_hi:[1,0]
	v_pk_mul_f32 v[98:99], v[98:99], v[246:247] op_sel_hi:[1,0]
	v_pk_mul_f32 v[108:109], v[228:229], v[108:109]
	v_pk_mul_f32 v[110:111], v[230:231], v[110:111]
	v_pk_mul_f32 v[104:105], v[232:233], v[104:105]
	v_pk_mul_f32 v[106:107], v[234:235], v[106:107]
	v_pk_mul_f32 v[100:101], v[236:237], v[100:101]
	v_pk_mul_f32 v[102:103], v[238:239], v[102:103]
	v_pk_mul_f32 v[96:97], v[240:241], v[96:97]
	v_pk_mul_f32 v[98:99], v[242:243], v[98:99]
	global_store_dwordx4 v[198:199], v[108:111], off
	global_store_dwordx4 v[198:199], v[104:107], off offset:16
	global_store_dwordx4 v[198:199], v[100:103], off offset:512
	global_store_dwordx4 v[198:199], v[96:99], off offset:528
	v_lshl_add_u64 v[198:199], v[198:199], 0, s[98:99]
	v_pk_mul_f32 v[92:93], v[92:93], v[184:185] op_sel_hi:[1,0]
	v_pk_mul_f32 v[94:95], v[94:95], v[184:185] op_sel_hi:[1,0]
	v_pk_mul_f32 v[88:89], v[88:89], v[184:185] op_sel_hi:[1,0]
	v_pk_mul_f32 v[90:91], v[90:91], v[184:185] op_sel_hi:[1,0]
	v_pk_mul_f32 v[84:85], v[84:85], v[184:185] op_sel_hi:[1,0]
	v_pk_mul_f32 v[86:87], v[86:87], v[184:185] op_sel_hi:[1,0]
	v_pk_mul_f32 v[80:81], v[80:81], v[184:185] op_sel_hi:[1,0]
	v_pk_mul_f32 v[82:83], v[82:83], v[184:185] op_sel_hi:[1,0]
	v_pk_mul_f32 v[92:93], v[228:229], v[92:93]
	v_pk_mul_f32 v[94:95], v[230:231], v[94:95]
	v_pk_mul_f32 v[88:89], v[232:233], v[88:89]
	v_pk_mul_f32 v[90:91], v[234:235], v[90:91]
	v_pk_mul_f32 v[84:85], v[236:237], v[84:85]
	v_pk_mul_f32 v[86:87], v[238:239], v[86:87]
	v_pk_mul_f32 v[80:81], v[240:241], v[80:81]
	v_pk_mul_f32 v[82:83], v[242:243], v[82:83]
	global_store_dwordx4 v[198:199], v[92:95], off
	global_store_dwordx4 v[198:199], v[88:91], off offset:16
	global_store_dwordx4 v[198:199], v[84:87], off offset:512
	global_store_dwordx4 v[198:199], v[80:83], off offset:528
	v_lshl_add_u64 v[198:199], v[198:199], 0, s[98:99]
	v_pk_mul_f32 v[76:77], v[76:77], v[186:187] op_sel_hi:[1,0]
	v_pk_mul_f32 v[78:79], v[78:79], v[186:187] op_sel_hi:[1,0]
	v_pk_mul_f32 v[72:73], v[72:73], v[186:187] op_sel_hi:[1,0]
	v_pk_mul_f32 v[74:75], v[74:75], v[186:187] op_sel_hi:[1,0]
	v_pk_mul_f32 v[68:69], v[68:69], v[186:187] op_sel_hi:[1,0]
	v_pk_mul_f32 v[70:71], v[70:71], v[186:187] op_sel_hi:[1,0]
; __device__ __forceinline__ void phase15(const Params& P) {
;     ...
;     while (row < NL) {
;         f32x4 v[4]; const float sc = sn;
; #pragma unroll
;         for (int j = 0; j < 4; ++j) v[j] = vn[j];
;         const int nrow = row + stride;
;         if (nrow < NL) { sn = ss4[nrow];
; #pragma unroll
;             for (int j = 0; j < 4; ++j) vn[j] = ((const f32x4*)(P.out + (size_t)nrow * 1024))[lane + 64 * j]; }
;         const float rstd = rsqrtf(sc * (1.f / 1024.f) + 1e-6f);
;         f32x4* o = (f32x4*)(P.out + (size_t)row * 1024);
; #pragma unroll
;         for (int j = 0; j < 4; ++j) o[lane + 64 * j] = (v[j] * rstd) * fn[j];
;         row = nrow;
;     }
	v_pk_mul_f32 v[64:65], v[64:65], v[186:187] op_sel_hi:[1,0]
	v_pk_mul_f32 v[66:67], v[66:67], v[186:187] op_sel_hi:[1,0]
	v_pk_mul_f32 v[76:77], v[228:229], v[76:77]
	v_pk_mul_f32 v[78:79], v[230:231], v[78:79]
	v_pk_mul_f32 v[72:73], v[232:233], v[72:73]
	v_pk_mul_f32 v[74:75], v[234:235], v[74:75]
	v_pk_mul_f32 v[68:69], v[236:237], v[68:69]
	v_pk_mul_f32 v[70:71], v[238:239], v[70:71]
	v_pk_mul_f32 v[64:65], v[240:241], v[64:65]
	v_pk_mul_f32 v[66:67], v[242:243], v[66:67]
	global_store_dwordx4 v[198:199], v[76:79], off
	global_store_dwordx4 v[198:199], v[72:75], off offset:16
	global_store_dwordx4 v[198:199], v[68:71], off offset:512
	global_store_dwordx4 v[198:199], v[64:67], off offset:528
	v_lshl_add_u64 v[198:199], v[198:199], 0, s[100:101]
	v_pk_mul_f32 v[60:61], v[60:61], v[188:189] op_sel_hi:[1,0]
	v_pk_mul_f32 v[62:63], v[62:63], v[188:189] op_sel_hi:[1,0]
	v_pk_mul_f32 v[56:57], v[56:57], v[188:189] op_sel_hi:[1,0]
	v_pk_mul_f32 v[58:59], v[58:59], v[188:189] op_sel_hi:[1,0]
	v_pk_mul_f32 v[52:53], v[52:53], v[188:189] op_sel_hi:[1,0]
	v_pk_mul_f32 v[54:55], v[54:55], v[188:189] op_sel_hi:[1,0]
	v_pk_mul_f32 v[48:49], v[48:49], v[188:189] op_sel_hi:[1,0]
	v_pk_mul_f32 v[50:51], v[50:51], v[188:189] op_sel_hi:[1,0]
	v_pk_mul_f32 v[60:61], v[228:229], v[60:61]
	v_pk_mul_f32 v[62:63], v[230:231], v[62:63]
	v_pk_mul_f32 v[56:57], v[232:233], v[56:57]
	v_pk_mul_f32 v[58:59], v[234:235], v[58:59]
	v_pk_mul_f32 v[52:53], v[236:237], v[52:53]
	v_pk_mul_f32 v[54:55], v[238:239], v[54:55]
	v_pk_mul_f32 v[48:49], v[240:241], v[48:49]
	v_pk_mul_f32 v[50:51], v[242:243], v[50:51]
	global_store_dwordx4 v[198:199], v[60:63], off
	global_store_dwordx4 v[198:199], v[56:59], off offset:16
	global_store_dwordx4 v[198:199], v[52:55], off offset:512
	global_store_dwordx4 v[198:199], v[48:51], off offset:528
	v_lshl_add_u64 v[198:199], v[198:199], 0, s[98:99]
	v_pk_mul_f32 v[44:45], v[44:45], v[190:191] op_sel_hi:[1,0]
	v_pk_mul_f32 v[46:47], v[46:47], v[190:191] op_sel_hi:[1,0]
	v_pk_mul_f32 v[40:41], v[40:41], v[190:191] op_sel_hi:[1,0]
	v_pk_mul_f32 v[42:43], v[42:43], v[190:191] op_sel_hi:[1,0]
	v_pk_mul_f32 v[36:37], v[36:37], v[190:191] op_sel_hi:[1,0]
	v_pk_mul_f32 v[38:39], v[38:39], v[190:191] op_sel_hi:[1,0]
	v_pk_mul_f32 v[32:33], v[32:33], v[190:191] op_sel_hi:[1,0]
	v_pk_mul_f32 v[34:35], v[34:35], v[190:191] op_sel_hi:[1,0]
	v_pk_mul_f32 v[44:45], v[228:229], v[44:45]
	v_pk_mul_f32 v[46:47], v[230:231], v[46:47]
	v_pk_mul_f32 v[40:41], v[232:233], v[40:41]
	v_pk_mul_f32 v[42:43], v[234:235], v[42:43]
	v_pk_mul_f32 v[36:37], v[236:237], v[36:37]
	v_pk_mul_f32 v[38:39], v[238:239], v[38:39]
	v_pk_mul_f32 v[32:33], v[240:241], v[32:33]
	v_pk_mul_f32 v[34:35], v[242:243], v[34:35]
	global_store_dwordx4 v[198:199], v[44:47], off
	global_store_dwordx4 v[198:199], v[40:43], off offset:16
	global_store_dwordx4 v[198:199], v[36:39], off offset:512
	global_store_dwordx4 v[198:199], v[32:35], off offset:528
	v_lshl_add_u64 v[198:199], v[198:199], 0, s[98:99]
	v_pk_mul_f32 v[28:29], v[28:29], v[192:193] op_sel_hi:[1,0]
	v_pk_mul_f32 v[30:31], v[30:31], v[192:193] op_sel_hi:[1,0]
	v_pk_mul_f32 v[24:25], v[24:25], v[192:193] op_sel_hi:[1,0]
	v_pk_mul_f32 v[26:27], v[26:27], v[192:193] op_sel_hi:[1,0]
	v_pk_mul_f32 v[20:21], v[20:21], v[192:193] op_sel_hi:[1,0]
	v_pk_mul_f32 v[22:23], v[22:23], v[192:193] op_sel_hi:[1,0]
	v_pk_mul_f32 v[16:17], v[16:17], v[192:193] op_sel_hi:[1,0]
	v_pk_mul_f32 v[18:19], v[18:19], v[192:193] op_sel_hi:[1,0]
	v_pk_mul_f32 v[28:29], v[228:229], v[28:29]
	v_pk_mul_f32 v[30:31], v[230:231], v[30:31]
	v_pk_mul_f32 v[24:25], v[232:233], v[24:25]
	v_pk_mul_f32 v[26:27], v[234:235], v[26:27]
	v_pk_mul_f32 v[20:21], v[236:237], v[20:21]
	v_pk_mul_f32 v[22:23], v[238:239], v[22:23]
	v_pk_mul_f32 v[16:17], v[240:241], v[16:17]
	v_pk_mul_f32 v[18:19], v[242:243], v[18:19]
	global_store_dwordx4 v[198:199], v[28:31], off
	global_store_dwordx4 v[198:199], v[24:27], off offset:16
	global_store_dwordx4 v[198:199], v[20:23], off offset:512
	global_store_dwordx4 v[198:199], v[16:19], off offset:528
	v_lshl_add_u64 v[198:199], v[198:199], 0, s[98:99]
	v_pk_mul_f32 v[12:13], v[12:13], v[194:195] op_sel_hi:[1,0]
	v_pk_mul_f32 v[14:15], v[14:15], v[194:195] op_sel_hi:[1,0]
	v_pk_mul_f32 v[8:9], v[8:9], v[194:195] op_sel_hi:[1,0]
	v_pk_mul_f32 v[10:11], v[10:11], v[194:195] op_sel_hi:[1,0]
	v_pk_mul_f32 v[4:5], v[4:5], v[194:195] op_sel_hi:[1,0]
	v_pk_mul_f32 v[6:7], v[6:7], v[194:195] op_sel_hi:[1,0]
	v_pk_mul_f32 v[0:1], v[0:1], v[194:195] op_sel_hi:[1,0]
	v_pk_mul_f32 v[2:3], v[2:3], v[194:195] op_sel_hi:[1,0]
	v_pk_mul_f32 v[12:13], v[228:229], v[12:13]
	v_pk_mul_f32 v[14:15], v[230:231], v[14:15]
	v_pk_mul_f32 v[8:9], v[232:233], v[8:9]
	v_pk_mul_f32 v[10:11], v[234:235], v[10:11]
	v_pk_mul_f32 v[4:5], v[236:237], v[4:5]
	v_pk_mul_f32 v[6:7], v[238:239], v[6:7]
	v_pk_mul_f32 v[0:1], v[240:241], v[0:1]
	v_pk_mul_f32 v[2:3], v[242:243], v[2:3]
	global_store_dwordx4 v[198:199], v[12:15], off
	global_store_dwordx4 v[198:199], v[8:11], off offset:16
	global_store_dwordx4 v[198:199], v[4:7], off offset:512
	global_store_dwordx4 v[198:199], v[0:3], off offset:528
	s_mov_b64 s[14:15], exec
	s_branch .LBB0_1691

; #define RUN(n, call) if (PHOK(n) && P.ph_lo <= n && n < P.ph_hi) { call; if (n + 1 < P.ph_hi) { if (n == 0) { grid.sync(); xb = xcd_barrier_post(bar, (volatile LAS3 unsigned*)&xb_words); } else xcd_barrier(xb); } }
; __global__ void __launch_bounds__(512, 2) mega(Params P) {
;     ...
;     RUN(14, phase_ffn_down<0>(P, lds, OFF_WDN2))
;     RUN(15, phase15(P))
; }
.LBB0_1768:
.LBB0_1828:
	s_endpgm
